# F epilogue: conv-weight and ssq loads issued together (one memory round trip per unit instead of two), on top of K-loop rebalancing
# speedup vs baseline: 1.0037x; 1.0037x over previous
.LBB0_919:
	v_lshl_add_u64 v[154:155], s[6:7], 0, v[164:165]
	s_add_i32 m0, s43, 0xc000
	ds_read_b128 v[146:149], v253
	ds_read_b128 v[150:153], v253 offset:1024
	ds_read_b128 v[168:171], v253 offset:2048
	ds_read_b128 v[172:175], v253 offset:3072
	ds_read_b128 v[176:179], v253 offset:4096
	ds_read_b128 v[180:183], v253 offset:5120
	ds_read_b128 v[184:187], v253 offset:6144
	ds_read_b128 v[190:193], v253 offset:7168
	global_load_lds_dwordx4 v[154:155], off
	s_add_i32 m0, s43, 0xe000
	v_lshl_add_u64 v[154:155], s[6:7], 0, v[166:167]
	global_load_lds_dwordx4 v[154:155], off
	s_waitcnt lgkmcnt(8)
	s_barrier
	s_waitcnt lgkmcnt(0)
	v_mfma_f32_16x16x32_bf16 v[126:129], v[130:133], v[146:149], v[126:129]
	v_mfma_f32_16x16x32_bf16 v[70:73], v[138:141], v[146:149], v[70:73]
	v_mfma_f32_16x16x32_bf16 v[122:125], v[130:133], v[168:171], v[122:125]
	v_mfma_f32_16x16x32_bf16 v[74:77], v[138:141], v[168:171], v[74:77]
	v_mfma_f32_16x16x32_bf16 v[114:117], v[130:133], v[176:179], v[114:117]
	v_mfma_f32_16x16x32_bf16 v[66:69], v[138:141], v[176:179], v[66:69]
	v_mfma_f32_16x16x32_bf16 v[110:113], v[130:133], v[184:187], v[110:113]
	v_mfma_f32_16x16x32_bf16 v[78:81], v[138:141], v[184:187], v[78:81]
	v_mfma_f32_16x16x32_bf16 v[126:129], v[134:137], v[150:153], v[126:129]
	v_mfma_f32_16x16x32_bf16 v[70:73], v[142:145], v[150:153], v[70:73]
	v_mfma_f32_16x16x32_bf16 v[122:125], v[134:137], v[172:175], v[122:125]
	v_mfma_f32_16x16x32_bf16 v[74:77], v[142:145], v[172:175], v[74:77]
	v_mfma_f32_16x16x32_bf16 v[114:117], v[134:137], v[180:183], v[114:117]
	v_mfma_f32_16x16x32_bf16 v[66:69], v[142:145], v[180:183], v[66:69]
	v_mfma_f32_16x16x32_bf16 v[110:113], v[134:137], v[190:193], v[110:113]
	v_mfma_f32_16x16x32_bf16 v[78:81], v[142:145], v[190:193], v[78:81]
	s_barrier
	s_add_i32 vcc_hi, 0, 0x14000
	s_add_i32 s6, vcc_lo, s39
	v_add_u32_e32 v0, vcc_hi, v254
	v_lshl_add_u64 v[154:155], s[90:91], 0, v[160:161]
	s_mov_b32 m0, s6
	ds_read_b128 v[194:197], v0
	ds_read_b128 v[198:201], v0 offset:1024
	ds_read_b128 v[202:205], v0 offset:2048
	ds_read_b128 v[206:209], v0 offset:3072
	global_load_lds_dwordx4 v[154:155], off
	s_add_i32 m0, s6, 0x2000
	v_lshl_add_u64 v[210:211], s[90:91], 0, v[156:157]
	global_load_lds_dwordx4 v[210:211], off
	s_barrier
	s_waitcnt lgkmcnt(0)
	v_mfma_f32_16x16x32_bf16 v[118:121], v[194:197], v[146:149], v[118:121]
	v_mfma_f32_16x16x32_bf16 v[94:97], v[202:205], v[146:149], v[94:97]
	v_mfma_f32_16x16x32_bf16 v[106:109], v[194:197], v[168:171], v[106:109]
	v_mfma_f32_16x16x32_bf16 v[90:93], v[202:205], v[168:171], v[90:93]
	v_mfma_f32_16x16x32_bf16 v[102:105], v[194:197], v[176:179], v[102:105]
	v_mfma_f32_16x16x32_bf16 v[82:85], v[202:205], v[176:179], v[82:85]
	v_mfma_f32_16x16x32_bf16 v[98:101], v[194:197], v[184:187], v[98:101]
	v_mfma_f32_16x16x32_bf16 v[86:89], v[202:205], v[184:187], v[86:89]
	v_mfma_f32_16x16x32_bf16 v[118:121], v[198:201], v[150:153], v[118:121]
	v_mfma_f32_16x16x32_bf16 v[94:97], v[206:209], v[150:153], v[94:97]
	v_mfma_f32_16x16x32_bf16 v[106:109], v[198:201], v[172:175], v[106:109]
	v_mfma_f32_16x16x32_bf16 v[90:93], v[206:209], v[172:175], v[90:93]
	v_mfma_f32_16x16x32_bf16 v[102:105], v[198:201], v[180:183], v[102:105]
	v_mfma_f32_16x16x32_bf16 v[82:85], v[206:209], v[180:183], v[82:85]
	v_mfma_f32_16x16x32_bf16 v[98:101], v[198:201], v[190:193], v[98:101]
	v_mfma_f32_16x16x32_bf16 v[86:89], v[206:209], v[190:193], v[86:89]
	s_mov_b32 m0, s43
	v_lshl_add_u64 v[212:213], s[92:93], 0, v[162:163]
	s_barrier
	ds_read_b128 v[146:149], v253 offset:16384
	ds_read_b128 v[150:153], v253 offset:17408
	ds_read_b128 v[168:171], v253 offset:18432
	ds_read_b128 v[172:175], v253 offset:19456
	ds_read_b128 v[176:179], v253 offset:20480
	ds_read_b128 v[180:183], v253 offset:21504
	ds_read_b128 v[184:187], v253 offset:22528
	ds_read_b128 v[190:193], v253 offset:23552
	global_load_lds_dwordx4 v[212:213], off
	s_mov_b32 m0, s60
	v_lshl_add_u64 v[214:215], s[92:93], 0, v[158:159]
	global_load_lds_dwordx4 v[214:215], off
	s_waitcnt vmcnt(10)
	s_barrier
	s_waitcnt lgkmcnt(0)
	v_mfma_f32_16x16x32_bf16 v[62:65], v[130:133], v[146:149], v[62:65]
	v_mfma_f32_16x16x32_bf16 v[10:13], v[138:141], v[146:149], v[10:13]
	v_mfma_f32_16x16x32_bf16 v[58:61], v[130:133], v[168:171], v[58:61]
	v_mfma_f32_16x16x32_bf16 v[14:17], v[138:141], v[168:171], v[14:17]
	v_mfma_f32_16x16x32_bf16 v[54:57], v[130:133], v[176:179], v[54:57]
	v_mfma_f32_16x16x32_bf16 v[6:9], v[138:141], v[176:179], v[6:9]
	v_mfma_f32_16x16x32_bf16 v[42:45], v[130:133], v[184:187], v[42:45]
	v_mfma_f32_16x16x32_bf16 v[2:5], v[138:141], v[184:187], v[2:5]
	v_mfma_f32_16x16x32_bf16 v[62:65], v[134:137], v[150:153], v[62:65]
	v_mfma_f32_16x16x32_bf16 v[10:13], v[142:145], v[150:153], v[10:13]
	v_mfma_f32_16x16x32_bf16 v[58:61], v[134:137], v[172:175], v[58:61]
	v_mfma_f32_16x16x32_bf16 v[14:17], v[142:145], v[172:175], v[14:17]
	v_mfma_f32_16x16x32_bf16 v[54:57], v[134:137], v[180:183], v[54:57]
	v_mfma_f32_16x16x32_bf16 v[6:9], v[142:145], v[180:183], v[6:9]
	v_mfma_f32_16x16x32_bf16 v[42:45], v[134:137], v[190:193], v[42:45]
	v_mfma_f32_16x16x32_bf16 v[2:5], v[142:145], v[190:193], v[2:5]
	s_barrier
	s_add_u32 s6, s90, 0x40000
	s_addc_u32 s7, s91, 0
	s_add_i32 vcc_lo, vcc_hi, s39
	s_mov_b32 m0, vcc_lo
	v_lshl_add_u64 v[130:131], s[6:7], 0, v[160:161]
	global_load_lds_dwordx4 v[130:131], off
	s_add_i32 m0, vcc_lo, 0x2000
	v_lshl_add_u64 v[130:131], s[6:7], 0, v[156:157]
	global_load_lds_dwordx4 v[130:131], off
	s_add_i32 vcc_lo, 0, 0x18000
	v_add_u32_e32 v0, vcc_lo, v254
	ds_read_b128 v[130:133], v0
	ds_read_b128 v[134:137], v0 offset:1024
	ds_read_b128 v[138:141], v0 offset:2048
	ds_read_b128 v[142:145], v0 offset:3072
	s_waitcnt vmcnt(6)
	s_barrier
	v_mfma_f32_16x16x32_bf16 v[50:53], v[194:197], v[146:149], v[50:53]
	v_mfma_f32_16x16x32_bf16 v[26:29], v[202:205], v[146:149], v[26:29]
	v_mfma_f32_16x16x32_bf16 v[46:49], v[194:197], v[168:171], v[46:49]
	v_mfma_f32_16x16x32_bf16 v[30:33], v[202:205], v[168:171], v[30:33]
	v_mfma_f32_16x16x32_bf16 v[38:41], v[194:197], v[176:179], v[38:41]
	v_mfma_f32_16x16x32_bf16 v[22:25], v[202:205], v[176:179], v[22:25]
	v_mfma_f32_16x16x32_bf16 v[34:37], v[194:197], v[184:187], v[34:37]
	v_mfma_f32_16x16x32_bf16 v[18:21], v[202:205], v[184:187], v[18:21]
	v_mfma_f32_16x16x32_bf16 v[50:53], v[198:201], v[150:153], v[50:53]
	v_mfma_f32_16x16x32_bf16 v[26:29], v[206:209], v[150:153], v[26:29]
	v_mfma_f32_16x16x32_bf16 v[46:49], v[198:201], v[172:175], v[46:49]
	v_mfma_f32_16x16x32_bf16 v[30:33], v[206:209], v[172:175], v[30:33]
	v_mfma_f32_16x16x32_bf16 v[38:41], v[198:201], v[180:183], v[38:41]
	v_mfma_f32_16x16x32_bf16 v[22:25], v[206:209], v[180:183], v[22:25]
	v_mfma_f32_16x16x32_bf16 v[34:37], v[198:201], v[190:193], v[34:37]
	v_mfma_f32_16x16x32_bf16 v[18:21], v[206:209], v[190:193], v[18:21]
	s_barrier
	s_add_u32 s6, s92, 0x40000
	s_addc_u32 s7, s93, 0
	s_mov_b32 m0, s61
	v_lshl_add_u64 v[194:195], s[6:7], 0, v[162:163]
	ds_read_b128 v[146:149], v253 offset:32768
	ds_read_b128 v[150:153], v253 offset:33792
	ds_read_b128 v[168:171], v253 offset:34816
	ds_read_b128 v[172:175], v253 offset:35840
	ds_read_b128 v[176:179], v253 offset:36864
	ds_read_b128 v[180:183], v253 offset:37888
	ds_read_b128 v[184:187], v253 offset:38912
	ds_read_b128 v[190:193], v253 offset:39936
	global_load_lds_dwordx4 v[194:195], off
	s_mov_b32 m0, s72
	v_lshl_add_u64 v[194:195], s[6:7], 0, v[158:159]
	global_load_lds_dwordx4 v[194:195], off
	s_waitcnt lgkmcnt(8)
	s_barrier
	s_waitcnt lgkmcnt(0)
	v_mfma_f32_16x16x32_bf16 v[126:129], v[130:133], v[146:149], v[126:129]
	v_mfma_f32_16x16x32_bf16 v[70:73], v[138:141], v[146:149], v[70:73]
	v_mfma_f32_16x16x32_bf16 v[122:125], v[130:133], v[168:171], v[122:125]
	v_mfma_f32_16x16x32_bf16 v[74:77], v[138:141], v[168:171], v[74:77]
	v_mfma_f32_16x16x32_bf16 v[114:117], v[130:133], v[176:179], v[114:117]
	v_mfma_f32_16x16x32_bf16 v[66:69], v[138:141], v[176:179], v[66:69]
	v_mfma_f32_16x16x32_bf16 v[110:113], v[130:133], v[184:187], v[110:113]
	v_mfma_f32_16x16x32_bf16 v[78:81], v[138:141], v[184:187], v[78:81]
	v_mfma_f32_16x16x32_bf16 v[126:129], v[134:137], v[150:153], v[126:129]
	v_mfma_f32_16x16x32_bf16 v[70:73], v[142:145], v[150:153], v[70:73]
	v_mfma_f32_16x16x32_bf16 v[122:125], v[134:137], v[172:175], v[122:125]
	v_mfma_f32_16x16x32_bf16 v[74:77], v[142:145], v[172:175], v[74:77]
	v_mfma_f32_16x16x32_bf16 v[114:117], v[134:137], v[180:183], v[114:117]
	v_mfma_f32_16x16x32_bf16 v[66:69], v[142:145], v[180:183], v[66:69]
	v_mfma_f32_16x16x32_bf16 v[110:113], v[134:137], v[190:193], v[110:113]
	v_mfma_f32_16x16x32_bf16 v[78:81], v[142:145], v[190:193], v[78:81]
	s_barrier
	s_add_i32 s92, 0, 0x1c000
	s_add_i32 s6, vcc_lo, s39
	v_add_u32_e32 v0, s92, v254
	v_lshl_add_u64 v[154:155], v[154:155], 0, s[40:41]
	s_mov_b32 m0, s6
	ds_read_b128 v[194:197], v0
	ds_read_b128 v[198:201], v0 offset:1024
	ds_read_b128 v[202:205], v0 offset:2048
	ds_read_b128 v[206:209], v0 offset:3072
	global_load_lds_dwordx4 v[154:155], off
	s_add_i32 m0, s6, 0x2000
	v_lshl_add_u64 v[154:155], v[210:211], 0, s[40:41]
	global_load_lds_dwordx4 v[154:155], off
	s_barrier
	s_waitcnt lgkmcnt(0)
	v_mfma_f32_16x16x32_bf16 v[118:121], v[194:197], v[146:149], v[118:121]
	v_mfma_f32_16x16x32_bf16 v[94:97], v[202:205], v[146:149], v[94:97]
	v_mfma_f32_16x16x32_bf16 v[106:109], v[194:197], v[168:171], v[106:109]
	v_mfma_f32_16x16x32_bf16 v[90:93], v[202:205], v[168:171], v[90:93]
	v_mfma_f32_16x16x32_bf16 v[102:105], v[194:197], v[176:179], v[102:105]
	v_mfma_f32_16x16x32_bf16 v[82:85], v[202:205], v[176:179], v[82:85]
	v_mfma_f32_16x16x32_bf16 v[98:101], v[194:197], v[184:187], v[98:101]
	v_mfma_f32_16x16x32_bf16 v[86:89], v[202:205], v[184:187], v[86:89]
	v_mfma_f32_16x16x32_bf16 v[118:121], v[198:201], v[150:153], v[118:121]
	v_mfma_f32_16x16x32_bf16 v[94:97], v[206:209], v[150:153], v[94:97]
	v_mfma_f32_16x16x32_bf16 v[106:109], v[198:201], v[172:175], v[106:109]
	v_mfma_f32_16x16x32_bf16 v[90:93], v[206:209], v[172:175], v[90:93]
	v_mfma_f32_16x16x32_bf16 v[102:105], v[198:201], v[180:183], v[102:105]
	v_mfma_f32_16x16x32_bf16 v[82:85], v[206:209], v[180:183], v[82:85]
	v_mfma_f32_16x16x32_bf16 v[98:101], v[198:201], v[190:193], v[98:101]
	v_mfma_f32_16x16x32_bf16 v[86:89], v[206:209], v[190:193], v[86:89]
	s_mov_b32 m0, s95
	v_lshl_add_u64 v[154:155], v[212:213], 0, s[40:41]
	s_barrier
	ds_read_b128 v[146:149], v253 offset:49152
	ds_read_b128 v[150:153], v253 offset:50176
	ds_read_b128 v[168:171], v253 offset:51200
	ds_read_b128 v[172:175], v253 offset:52224
	ds_read_b128 v[176:179], v253 offset:53248
	ds_read_b128 v[180:183], v253 offset:54272
	ds_read_b128 v[184:187], v253 offset:55296
	ds_read_b128 v[190:193], v253 offset:56320
	global_load_lds_dwordx4 v[154:155], off
	s_mov_b32 m0, s96
	v_lshl_add_u64 v[154:155], v[214:215], 0, s[40:41]
	global_load_lds_dwordx4 v[154:155], off
	s_waitcnt vmcnt(10)
	s_barrier
	s_waitcnt lgkmcnt(0)
	v_mfma_f32_16x16x32_bf16 v[62:65], v[130:133], v[146:149], v[62:65]
	v_mfma_f32_16x16x32_bf16 v[10:13], v[138:141], v[146:149], v[10:13]
	v_mfma_f32_16x16x32_bf16 v[58:61], v[130:133], v[168:171], v[58:61]
	v_mfma_f32_16x16x32_bf16 v[14:17], v[138:141], v[168:171], v[14:17]
	v_mfma_f32_16x16x32_bf16 v[54:57], v[130:133], v[176:179], v[54:57]
	v_mfma_f32_16x16x32_bf16 v[6:9], v[138:141], v[176:179], v[6:9]
	v_mfma_f32_16x16x32_bf16 v[42:45], v[130:133], v[184:187], v[42:45]
	v_mfma_f32_16x16x32_bf16 v[2:5], v[138:141], v[184:187], v[2:5]
	v_mfma_f32_16x16x32_bf16 v[62:65], v[134:137], v[150:153], v[62:65]
	v_mfma_f32_16x16x32_bf16 v[10:13], v[142:145], v[150:153], v[10:13]
	v_mfma_f32_16x16x32_bf16 v[58:61], v[134:137], v[172:175], v[58:61]
	v_mfma_f32_16x16x32_bf16 v[14:17], v[142:145], v[172:175], v[14:17]
	v_mfma_f32_16x16x32_bf16 v[54:57], v[134:137], v[180:183], v[54:57]
	v_mfma_f32_16x16x32_bf16 v[6:9], v[142:145], v[180:183], v[6:9]
	v_mfma_f32_16x16x32_bf16 v[42:45], v[134:137], v[190:193], v[42:45]
	v_mfma_f32_16x16x32_bf16 v[2:5], v[142:145], v[190:193], v[2:5]
	s_barrier
	s_add_u32 s6, s90, 0x40080
	s_addc_u32 s7, s91, 0
	s_add_i32 s90, s92, s39
	s_mov_b32 m0, s90
	v_lshl_add_u64 v[130:131], s[6:7], 0, v[160:161]
	global_load_lds_dwordx4 v[130:131], off
	s_add_i32 m0, s90, 0x2000
	v_lshl_add_u64 v[130:131], s[6:7], 0, v[156:157]
	global_load_lds_dwordx4 v[130:131], off
	s_add_i32 vcc_lo, 0, 0x10000
	v_add_u32_e32 v0, vcc_lo, v254
	ds_read_b128 v[130:133], v0
	ds_read_b128 v[134:137], v0 offset:1024
	ds_read_b128 v[138:141], v0 offset:2048
	ds_read_b128 v[142:145], v0 offset:3072
	s_waitcnt vmcnt(6)
	s_barrier
	v_mfma_f32_16x16x32_bf16 v[50:53], v[194:197], v[146:149], v[50:53]
	v_mfma_f32_16x16x32_bf16 v[26:29], v[202:205], v[146:149], v[26:29]
	v_mfma_f32_16x16x32_bf16 v[46:49], v[194:197], v[168:171], v[46:49]
	v_mfma_f32_16x16x32_bf16 v[30:33], v[202:205], v[168:171], v[30:33]
	v_mfma_f32_16x16x32_bf16 v[38:41], v[194:197], v[176:179], v[38:41]
	v_mfma_f32_16x16x32_bf16 v[22:25], v[202:205], v[176:179], v[22:25]
	v_mfma_f32_16x16x32_bf16 v[34:37], v[194:197], v[184:187], v[34:37]
	v_mfma_f32_16x16x32_bf16 v[18:21], v[202:205], v[184:187], v[18:21]
	v_mfma_f32_16x16x32_bf16 v[50:53], v[198:201], v[150:153], v[50:53]
	v_mfma_f32_16x16x32_bf16 v[26:29], v[206:209], v[150:153], v[26:29]
	v_mfma_f32_16x16x32_bf16 v[46:49], v[198:201], v[172:175], v[46:49]
	v_mfma_f32_16x16x32_bf16 v[30:33], v[206:209], v[172:175], v[30:33]
	v_mfma_f32_16x16x32_bf16 v[38:41], v[198:201], v[180:183], v[38:41]
	v_mfma_f32_16x16x32_bf16 v[22:25], v[206:209], v[180:183], v[22:25]
	v_mfma_f32_16x16x32_bf16 v[34:37], v[198:201], v[190:193], v[34:37]
	v_mfma_f32_16x16x32_bf16 v[18:21], v[206:209], v[190:193], v[18:21]
	s_add_i32 s45, s45, 2
	s_add_u32 s28, s28, 0x100
	s_addc_u32 s29, s29, 0
	s_mov_b64 s[6:7], s[88:89]
	s_add_u32 s88, s6, 0x100
	s_addc_u32 s89, s7, 0
	s_cmp_eq_u32 s45, 12
	s_cselect_b32 s93, s17, s89
	s_cselect_b32 s92, s22, s88
	s_cselect_b32 s91, s15, s29
	s_cselect_b32 s90, s23, s28
	s_cmp_gt_u32 s45, 13
	s_barrier
	s_cbranch_scc0 .LBB0_919
	s_waitcnt lgkmcnt(0)
	v_mov_b32_e32 v131, v252
	s_lshl_b32 s88, s5, 7
	v_bfe_u32 v130, v131, 4, 2
	v_and_b32_e32 v134, 15, v131
	v_lshlrev_b32_e32 v0, 4, v130
	s_ashr_i32 s89, s88, 31
	s_lshl_b32 s15, s4, 8
	v_or3_b32 v135, v0, s97, v134
	s_lshl_b64 s[4:5], s[88:89], 2
	v_lshrrev_b32_e32 v140, 1, v135
	s_add_u32 s4, s73, s4
	s_addc_u32 s5, s74, s5
	v_lshlrev_b32_e32 v0, 2, v140
	v_and_b32_e32 v144, 1, v131
	v_lshl_add_u64 v[132:133], s[4:5], 0, v[0:1]
	v_cmp_eq_u32_e32 vcc, 1, v144
	v_mov_b32_e32 v0, 0xb00
	s_movk_i32 s4, 0x5000
	v_cndmask_b32_e32 v141, 0, v0, vcc
	v_lshlrev_b32_e32 v0, 2, v141
	v_lshl_add_u64 v[132:133], v[132:133], 0, v[0:1]
	v_add_co_u32_e32 v138, vcc, s4, v132
	s_mov_b32 s4, 0xb000
	s_nop 0
	v_addc_co_u32_e32 v139, vcc, 0, v133, vcc
	global_load_dword v136, v[132:133], off
	global_load_dword v137, v[138:139], off offset:2048
	v_add_co_u32_e32 v132, vcc, s4, v132
	v_add_u32_e32 v0, s88, v141
	s_nop 0
	v_addc_co_u32_e32 v133, vcc, 0, v133, vcc
	global_load_dword v138, v[132:133], off
	v_or_b32_e32 v132, v140, v0
	v_ashrrev_i32_e32 v133, 31, v132
	v_lshl_add_u64 v[132:133], v[132:133], 2, s[12:13]
	global_load_dword v139, v[132:133], off
	v_lshl_add_u32 v152, v135, 4, s78
	v_and_b32_e32 v135, 63, v131
	v_cmp_eq_u32_e32 vcc, 0, v144
	v_or_b32_e32 v0, s97, v135
	v_lshrrev_b32_e32 v0, 1, v0
	v_and_or_b32 v131, v0, 63, s55
	v_add_u32_e32 v132, s15, v131
	v_ashrrev_i32_e32 v133, 31, v132
	v_lshlrev_b64 v[132:133], 6, v[132:133]
	v_lshl_add_u64 v[132:133], s[10:11], 0, v[132:133]
	v_lshlrev_b32_e32 v0, 5, v144
	v_lshl_add_u64 v[132:133], v[132:133], 0, v[0:1]
	global_load_dwordx4 v[148:151], v[132:133], off offset:16
	global_load_dwordx4 v[140:143], v[132:133], off
	s_waitcnt vmcnt(2)
	ds_write_b128 v152, v[136:139]
	s_waitcnt vmcnt(0)
	v_add_f32_e32 v133, v150, v151
	v_add_f32_e32 v0, v140, v141
	v_add_f32_e32 v132, v142, v143
	v_add_f32_e32 v0, v0, v132
	v_add_f32_e32 v132, v148, v149
	v_add_f32_e32 v132, v132, v133
	v_add_f32_e32 v0, v0, v132
	v_lshlrev_b32_e32 v132, 2, v135
	v_xor_b32_e32 v132, 4, v132
	ds_bpermute_b32 v132, v132, v0
	s_and_saveexec_b64 s[4:5], vcc
	s_cbranch_execz .LBB0_922
	s_waitcnt lgkmcnt(0)
	v_add_f32_e32 v0, v0, v132
	v_mov_b32_e32 v132, 0x358637bd
	v_fmamk_f32 v0, v0, 0x3a800000, v132
	s_mov_b32 s6, 0x800000
	v_mul_f32_e32 v132, 0x4b800000, v0
	v_cmp_gt_f32_e32 vcc, s6, v0
	v_lshl_add_u32 v131, v131, 2, 0
	v_add_u32_e32 v131, 0x20000, v131
	v_cndmask_b32_e32 v0, v0, v132, vcc
	v_rsq_f32_e32 v0, v0
	s_nop 0
	v_mul_f32_e32 v132, 0x45800000, v0
	v_cndmask_b32_e32 v0, v0, v132, vcc
	ds_write_b32 v131, v0
